# rope (phase 3) hand-written: fixed item column per thread, rows through an 8-deep load ring
# baseline (speedup 1.0000x reference)
; #define TIDX tid_fn()
; __device__ __forceinline__ void ph_rope(const Params& P) {
;   h16* p = (h16*)(P.ws + O_P0);
;   const float* rc = (const float*)(P.ws + O_ROPE);
;   const float* rs = rc + (size_t)(SEQ + CTX_LEN) * 64;
;   const float kscale = 0.08838834764831845f;
;   constexpr int PER_ROW = 2 * RET_HEADS * 16;
;   const size_t total = (size_t)NT * PER_ROW;
; #pragma unroll 2
;   for (size_t i = (size_t)blockIdx.x * NTHR + TIDX; i < total; i += (size_t)gridDim.x * NTHR) {
;     const int row = (int)(i / PER_ROW), it = (int)(i % PER_ROW);
;     const int f4 = it % 16, hh = (it / 16) % RET_HEADS, qk = it / (16 * RET_HEADS);
;     int isc, b, t; row_decode(row, isc, b, t);
;     const int pos = isc ? SEQ + t : t;
;     h16* pr = p + (size_t)row * NP_EV + 3 * HY_CH + qk * RETW + hh * RET_HD + f4 * 4;
;     const h16x4 t1 = *(const h16x4*)pr, t2 = *(const h16x4*)(pr + 64);
;     const float4 c = *(const float4*)(rc + (size_t)pos * 64 + f4 * 4), s = *(const float4*)(rs + (size_t)pos * 64 + f4 * 4);
;     const float sc = qk ? kscale : 1.0f;
;     h16x4 o1, o2;
;     o1[0] = (h16)(((float)t1[0] * c.x - (float)t2[0] * s.x) * sc); o2[0] = (h16)(((float)t1[0] * s.x + (float)t2[0] * c.x) * sc);
;     o1[1] = (h16)(((float)t1[1] * c.y - (float)t2[1] * s.y) * sc); o2[1] = (h16)(((float)t1[1] * s.y + (float)t2[1] * c.y) * sc);
;     o1[2] = (h16)(((float)t1[2] * c.z - (float)t2[2] * s.z) * sc); o2[2] = (h16)(((float)t1[2] * s.z + (float)t2[2] * c.z) * sc);
;     o1[3] = (h16)(((float)t1[3] * c.w - (float)t2[3] * s.w) * sc); o2[3] = (h16)(((float)t1[3] * s.w + (float)t2[3] * c.w) * sc);
;     *(h16x4*)pr = o1; *(h16x4*)(pr + 64) = o2;
;   }
; }
.LBB0_522:
	s_mov_b64 s[8:9], exec
	s_mov_b32 s85, 0
	s_load_dwordx2 s[4:5], s[96:97], 0x178
	v_and_b32_e32 v3, 0xff, v0
	v_lshrrev_b32_e32 v6, 4, v3
	v_and_b32_e32 v7, 15, v3
	v_lshlrev_b32_e32 v1, 8, v6
	v_lshl_add_u32 v1, v7, 3, v1
	v_add_u32_e32 v1, 0x1800, v1
	v_lshlrev_b32_e32 v2, 4, v7
	v_cmp_gt_u32_e32 vcc, 0x80, v3
	v_mov_b32_e32 v4, 0x3db504f3
	v_mov_b32_e32 v6, 1.0
	v_cndmask_b32_e32 v4, v4, v6, vcc
	v_mov_b32_e32 v5, v4
	v_readfirstlane_b32 s22, v0
	s_lshr_b32 s22, s22, 8
	s_lshl_b32 s0, s2, 1
	s_add_u32 s22, s22, s0
	s_waitcnt lgkmcnt(0)
	s_mul_i32 s0, s22, 0x3800
	s_add_u32 s10, s4, 0x160cc000
	s_addc_u32 s11, s5, 0
	s_add_u32 s10, s10, s0
	s_addc_u32 s11, s11, 0
	s_mov_b64 s[12:13], s[10:11]
	s_lshl_b32 s0, s22, 8
	s_add_u32 s18, s4, 0x4c000
	s_addc_u32 s19, s5, 0
	s_add_u32 s18, s18, s0
	s_addc_u32 s19, s19, 0
	s_add_u32 s20, s18, 0x410000
	s_addc_u32 s21, s19, 0
	s_mov_b64 s[14:15], s[18:19]
	s_mov_b64 s[16:17], s[20:21]
	global_load_dwordx2 v[32:33], v1, s[10:11]
	global_load_dwordx2 v[34:35], v1, s[10:11] offset:128
	global_load_dwordx4 v[36:39], v2, s[14:15]
	global_load_dwordx4 v[40:43], v2, s[16:17]
	s_add_u32 s10, s10, 0x700000
	s_addc_u32 s11, s11, 0
	s_add_u32 s14, s14, 0x20000
	s_addc_u32 s15, s15, 0
	s_add_u32 s16, s16, 0x20000
	s_addc_u32 s17, s17, 0
	global_load_dwordx2 v[44:45], v1, s[10:11]
	global_load_dwordx2 v[46:47], v1, s[10:11] offset:128
	global_load_dwordx4 v[48:51], v2, s[14:15]
	global_load_dwordx4 v[52:55], v2, s[16:17]
	s_add_u32 s10, s10, 0x700000
	s_addc_u32 s11, s11, 0
	s_add_u32 s14, s14, 0x20000
	s_addc_u32 s15, s15, 0
	s_add_u32 s16, s16, 0x20000
	s_addc_u32 s17, s17, 0
	global_load_dwordx2 v[56:57], v1, s[10:11]
	global_load_dwordx2 v[58:59], v1, s[10:11] offset:128
	global_load_dwordx4 v[60:63], v2, s[14:15]
	global_load_dwordx4 v[64:67], v2, s[16:17]
	s_add_u32 s10, s10, 0x700000
	s_addc_u32 s11, s11, 0
	s_add_u32 s14, s14, 0x20000
	s_addc_u32 s15, s15, 0
	s_add_u32 s16, s16, 0x20000
	s_addc_u32 s17, s17, 0
	global_load_dwordx2 v[68:69], v1, s[10:11]
	global_load_dwordx2 v[70:71], v1, s[10:11] offset:128
	global_load_dwordx4 v[72:75], v2, s[14:15]
	global_load_dwordx4 v[76:79], v2, s[16:17]
	s_add_u32 s10, s10, 0x700000
	s_addc_u32 s11, s11, 0
	s_add_u32 s14, s14, 0x20000
	s_addc_u32 s15, s15, 0
	s_add_u32 s16, s16, 0x20000
	s_addc_u32 s17, s17, 0
	global_load_dwordx2 v[80:81], v1, s[10:11]
	global_load_dwordx2 v[82:83], v1, s[10:11] offset:128
	global_load_dwordx4 v[84:87], v2, s[14:15]
	global_load_dwordx4 v[88:91], v2, s[16:17]
	s_add_u32 s10, s10, 0x700000
	s_addc_u32 s11, s11, 0
	s_add_u32 s14, s14, 0x20000
	s_addc_u32 s15, s15, 0
	s_add_u32 s16, s16, 0x20000
	s_addc_u32 s17, s17, 0
	global_load_dwordx2 v[92:93], v1, s[10:11]
	global_load_dwordx2 v[94:95], v1, s[10:11] offset:128
	global_load_dwordx4 v[96:99], v2, s[14:15]
	global_load_dwordx4 v[100:103], v2, s[16:17]
	s_add_u32 s10, s10, 0x700000
	s_addc_u32 s11, s11, 0
	s_add_u32 s14, s14, 0x20000
	s_addc_u32 s15, s15, 0
	s_add_u32 s16, s16, 0x20000
	s_addc_u32 s17, s17, 0
	global_load_dwordx2 v[104:105], v1, s[10:11]
	global_load_dwordx2 v[106:107], v1, s[10:11] offset:128
	global_load_dwordx4 v[108:111], v2, s[14:15]
	global_load_dwordx4 v[112:115], v2, s[16:17]
	s_add_u32 s10, s10, 0x700000
	s_addc_u32 s11, s11, 0
	s_add_u32 s14, s14, 0x20000
	s_addc_u32 s15, s15, 0
	s_add_u32 s16, s16, 0x20000
	s_addc_u32 s17, s17, 0
	global_load_dwordx2 v[116:117], v1, s[10:11]
	global_load_dwordx2 v[118:119], v1, s[10:11] offset:128
	global_load_dwordx4 v[120:123], v2, s[14:15]
	global_load_dwordx4 v[124:127], v2, s[16:17]
	s_add_u32 s10, s10, 0x700000
	s_addc_u32 s11, s11, 0
	s_add_u32 s14, s14, 0x20000
	s_addc_u32 s15, s15, 0
	s_add_u32 s16, s16, 0x20000
	s_addc_u32 s17, s17, 0
	s_waitcnt vmcnt(28)
	v_cvt_f32_f16_e32 v16, v32
	v_cvt_f32_f16_sdwa v17, v32 dst_sel:DWORD dst_unused:UNUSED_PAD src0_sel:WORD_1
	v_cvt_f32_f16_e32 v20, v34
	v_cvt_f32_f16_sdwa v21, v34 dst_sel:DWORD dst_unused:UNUSED_PAD src0_sel:WORD_1
	v_cvt_f32_f16_e32 v18, v33
	v_cvt_f32_f16_sdwa v19, v33 dst_sel:DWORD dst_unused:UNUSED_PAD src0_sel:WORD_1
	v_cvt_f32_f16_e32 v22, v35
	v_cvt_f32_f16_sdwa v23, v35 dst_sel:DWORD dst_unused:UNUSED_PAD src0_sel:WORD_1
	v_pk_mul_f32 v[24:25], v[16:17], v[36:37]
	v_pk_mul_f32 v[28:29], v[16:17], v[40:41]
	v_pk_mul_f32 v[26:27], v[18:19], v[38:39]
	v_pk_mul_f32 v[30:31], v[18:19], v[42:43]
	v_pk_fma_f32 v[24:25], v[20:21], v[40:41], v[24:25] neg_lo:[1,0,0] neg_hi:[1,0,0]
	v_pk_fma_f32 v[28:29], v[20:21], v[36:37], v[28:29]
	v_pk_fma_f32 v[26:27], v[22:23], v[42:43], v[26:27] neg_lo:[1,0,0] neg_hi:[1,0,0]
	v_pk_fma_f32 v[30:31], v[22:23], v[38:39], v[30:31]
	v_pk_mul_f32 v[24:25], v[24:25], v[4:5]
	v_pk_mul_f32 v[28:29], v[28:29], v[4:5]
	v_pk_mul_f32 v[26:27], v[26:27], v[4:5]
	v_pk_mul_f32 v[30:31], v[30:31], v[4:5]
	v_cvt_pk_f16_f32 v8, v24, v25
	v_cvt_pk_f16_f32 v9, v26, v27
	v_cvt_pk_f16_f32 v10, v28, v29
	v_cvt_pk_f16_f32 v11, v30, v31
	global_store_dwordx2 v1, v[8:9], s[12:13]
	global_store_dwordx2 v1, v[10:11], s[12:13] offset:128
	s_add_u32 s12, s12, 0x700000
	s_addc_u32 s13, s13, 0
	global_load_dwordx2 v[32:33], v1, s[10:11]
	global_load_dwordx2 v[34:35], v1, s[10:11] offset:128
	global_load_dwordx4 v[36:39], v2, s[14:15]
	global_load_dwordx4 v[40:43], v2, s[16:17]
	s_add_u32 s10, s10, 0x700000
	s_addc_u32 s11, s11, 0
	s_add_u32 s14, s14, 0x20000
	s_addc_u32 s15, s15, 0
	s_add_u32 s16, s16, 0x20000
	s_addc_u32 s17, s17, 0
	s_waitcnt vmcnt(30)
; #define TIDX tid_fn()
; __device__ __forceinline__ void ph_rope(const Params& P) {
;     ...
;   for (size_t i = (size_t)blockIdx.x * NTHR + TIDX; i < total; i += (size_t)gridDim.x * NTHR) {
;     const int row = (int)(i / PER_ROW), it = (int)(i % PER_ROW);
;     const int f4 = it % 16, hh = (it / 16) % RET_HEADS, qk = it / (16 * RET_HEADS);
;     int isc, b, t; row_decode(row, isc, b, t);
;     const int pos = isc ? SEQ + t : t;
;     h16* pr = p + (size_t)row * NP_EV + 3 * HY_CH + qk * RETW + hh * RET_HD + f4 * 4;
;     const h16x4 t1 = *(const h16x4*)pr, t2 = *(const h16x4*)(pr + 64);
;     const float4 c = *(const float4*)(rc + (size_t)pos * 64 + f4 * 4), s = *(const float4*)(rs + (size_t)pos * 64 + f4 * 4);
;     const float sc = qk ? kscale : 1.0f;
;     h16x4 o1, o2;
;     o1[0] = (h16)(((float)t1[0] * c.x - (float)t2[0] * s.x) * sc); o2[0] = (h16)(((float)t1[0] * s.x + (float)t2[0] * c.x) * sc);
;     o1[1] = (h16)(((float)t1[1] * c.y - (float)t2[1] * s.y) * sc); o2[1] = (h16)(((float)t1[1] * s.y + (float)t2[1] * c.y) * sc);
;     o1[2] = (h16)(((float)t1[2] * c.z - (float)t2[2] * s.z) * sc); o2[2] = (h16)(((float)t1[2] * s.z + (float)t2[2] * c.z) * sc);
;     o1[3] = (h16)(((float)t1[3] * c.w - (float)t2[3] * s.w) * sc); o2[3] = (h16)(((float)t1[3] * s.w + (float)t2[3] * c.w) * sc);
;     *(h16x4*)pr = o1; *(h16x4*)(pr + 64) = o2;
;   }
	v_cvt_f32_f16_e32 v16, v44
	v_cvt_f32_f16_sdwa v17, v44 dst_sel:DWORD dst_unused:UNUSED_PAD src0_sel:WORD_1
	v_cvt_f32_f16_e32 v20, v46
	v_cvt_f32_f16_sdwa v21, v46 dst_sel:DWORD dst_unused:UNUSED_PAD src0_sel:WORD_1
	v_cvt_f32_f16_e32 v18, v45
	v_cvt_f32_f16_sdwa v19, v45 dst_sel:DWORD dst_unused:UNUSED_PAD src0_sel:WORD_1
	v_cvt_f32_f16_e32 v22, v47
	v_cvt_f32_f16_sdwa v23, v47 dst_sel:DWORD dst_unused:UNUSED_PAD src0_sel:WORD_1
	v_pk_mul_f32 v[24:25], v[16:17], v[48:49]
	v_pk_mul_f32 v[28:29], v[16:17], v[52:53]
	v_pk_mul_f32 v[26:27], v[18:19], v[50:51]
	v_pk_mul_f32 v[30:31], v[18:19], v[54:55]
	v_pk_fma_f32 v[24:25], v[20:21], v[52:53], v[24:25] neg_lo:[1,0,0] neg_hi:[1,0,0]
	v_pk_fma_f32 v[28:29], v[20:21], v[48:49], v[28:29]
	v_pk_fma_f32 v[26:27], v[22:23], v[54:55], v[26:27] neg_lo:[1,0,0] neg_hi:[1,0,0]
	v_pk_fma_f32 v[30:31], v[22:23], v[50:51], v[30:31]
	v_pk_mul_f32 v[24:25], v[24:25], v[4:5]
	v_pk_mul_f32 v[28:29], v[28:29], v[4:5]
	v_pk_mul_f32 v[26:27], v[26:27], v[4:5]
	v_pk_mul_f32 v[30:31], v[30:31], v[4:5]
	v_cvt_pk_f16_f32 v12, v24, v25
	v_cvt_pk_f16_f32 v13, v26, v27
	v_cvt_pk_f16_f32 v14, v28, v29
	v_cvt_pk_f16_f32 v15, v30, v31
	global_store_dwordx2 v1, v[12:13], s[12:13]
	global_store_dwordx2 v1, v[14:15], s[12:13] offset:128
	s_add_u32 s12, s12, 0x700000
	s_addc_u32 s13, s13, 0
	global_load_dwordx2 v[44:45], v1, s[10:11]
	global_load_dwordx2 v[46:47], v1, s[10:11] offset:128
	global_load_dwordx4 v[48:51], v2, s[14:15]
	global_load_dwordx4 v[52:55], v2, s[16:17]
	s_add_u32 s10, s10, 0x700000
	s_addc_u32 s11, s11, 0
	s_add_u32 s14, s14, 0x20000
	s_addc_u32 s15, s15, 0
	s_add_u32 s16, s16, 0x20000
	s_addc_u32 s17, s17, 0
	s_waitcnt vmcnt(32)
	v_cvt_f32_f16_e32 v16, v56
	v_cvt_f32_f16_sdwa v17, v56 dst_sel:DWORD dst_unused:UNUSED_PAD src0_sel:WORD_1
	v_cvt_f32_f16_e32 v20, v58
	v_cvt_f32_f16_sdwa v21, v58 dst_sel:DWORD dst_unused:UNUSED_PAD src0_sel:WORD_1
	v_cvt_f32_f16_e32 v18, v57
	v_cvt_f32_f16_sdwa v19, v57 dst_sel:DWORD dst_unused:UNUSED_PAD src0_sel:WORD_1
	v_cvt_f32_f16_e32 v22, v59
	v_cvt_f32_f16_sdwa v23, v59 dst_sel:DWORD dst_unused:UNUSED_PAD src0_sel:WORD_1
	v_pk_mul_f32 v[24:25], v[16:17], v[60:61]
	v_pk_mul_f32 v[28:29], v[16:17], v[64:65]
	v_pk_mul_f32 v[26:27], v[18:19], v[62:63]
	v_pk_mul_f32 v[30:31], v[18:19], v[66:67]
	v_pk_fma_f32 v[24:25], v[20:21], v[64:65], v[24:25] neg_lo:[1,0,0] neg_hi:[1,0,0]
	v_pk_fma_f32 v[28:29], v[20:21], v[60:61], v[28:29]
	v_pk_fma_f32 v[26:27], v[22:23], v[66:67], v[26:27] neg_lo:[1,0,0] neg_hi:[1,0,0]
	v_pk_fma_f32 v[30:31], v[22:23], v[62:63], v[30:31]
	v_pk_mul_f32 v[24:25], v[24:25], v[4:5]
	v_pk_mul_f32 v[28:29], v[28:29], v[4:5]
	v_pk_mul_f32 v[26:27], v[26:27], v[4:5]
	v_pk_mul_f32 v[30:31], v[30:31], v[4:5]
	v_cvt_pk_f16_f32 v8, v24, v25
	v_cvt_pk_f16_f32 v9, v26, v27
	v_cvt_pk_f16_f32 v10, v28, v29
	v_cvt_pk_f16_f32 v11, v30, v31
	global_store_dwordx2 v1, v[8:9], s[12:13]
	global_store_dwordx2 v1, v[10:11], s[12:13] offset:128
	s_add_u32 s12, s12, 0x700000
	s_addc_u32 s13, s13, 0
	global_load_dwordx2 v[56:57], v1, s[10:11]
	global_load_dwordx2 v[58:59], v1, s[10:11] offset:128
	global_load_dwordx4 v[60:63], v2, s[14:15]
	global_load_dwordx4 v[64:67], v2, s[16:17]
	s_add_u32 s10, s10, 0x700000
	s_addc_u32 s11, s11, 0
	s_add_u32 s14, s14, 0x20000
	s_addc_u32 s15, s15, 0
	s_add_u32 s16, s16, 0x20000
	s_addc_u32 s17, s17, 0
	s_waitcnt vmcnt(34)
	v_cvt_f32_f16_e32 v16, v68
	v_cvt_f32_f16_sdwa v17, v68 dst_sel:DWORD dst_unused:UNUSED_PAD src0_sel:WORD_1
	v_cvt_f32_f16_e32 v20, v70
	v_cvt_f32_f16_sdwa v21, v70 dst_sel:DWORD dst_unused:UNUSED_PAD src0_sel:WORD_1
	v_cvt_f32_f16_e32 v18, v69
	v_cvt_f32_f16_sdwa v19, v69 dst_sel:DWORD dst_unused:UNUSED_PAD src0_sel:WORD_1
	v_cvt_f32_f16_e32 v22, v71
	v_cvt_f32_f16_sdwa v23, v71 dst_sel:DWORD dst_unused:UNUSED_PAD src0_sel:WORD_1
	v_pk_mul_f32 v[24:25], v[16:17], v[72:73]
	v_pk_mul_f32 v[28:29], v[16:17], v[76:77]
	v_pk_mul_f32 v[26:27], v[18:19], v[74:75]
	v_pk_mul_f32 v[30:31], v[18:19], v[78:79]
	v_pk_fma_f32 v[24:25], v[20:21], v[76:77], v[24:25] neg_lo:[1,0,0] neg_hi:[1,0,0]
	v_pk_fma_f32 v[28:29], v[20:21], v[72:73], v[28:29]
	v_pk_fma_f32 v[26:27], v[22:23], v[78:79], v[26:27] neg_lo:[1,0,0] neg_hi:[1,0,0]
	v_pk_fma_f32 v[30:31], v[22:23], v[74:75], v[30:31]
	v_pk_mul_f32 v[24:25], v[24:25], v[4:5]
	v_pk_mul_f32 v[28:29], v[28:29], v[4:5]
	v_pk_mul_f32 v[26:27], v[26:27], v[4:5]
	v_pk_mul_f32 v[30:31], v[30:31], v[4:5]
	v_cvt_pk_f16_f32 v12, v24, v25
	v_cvt_pk_f16_f32 v13, v26, v27
	v_cvt_pk_f16_f32 v14, v28, v29
	v_cvt_pk_f16_f32 v15, v30, v31
	global_store_dwordx2 v1, v[12:13], s[12:13]
	global_store_dwordx2 v1, v[14:15], s[12:13] offset:128
	s_add_u32 s12, s12, 0x700000
	s_addc_u32 s13, s13, 0
	global_load_dwordx2 v[68:69], v1, s[10:11]
	global_load_dwordx2 v[70:71], v1, s[10:11] offset:128
	global_load_dwordx4 v[72:75], v2, s[14:15]
	global_load_dwordx4 v[76:79], v2, s[16:17]
	s_add_u32 s10, s10, 0x700000
	s_addc_u32 s11, s11, 0
	s_add_u32 s14, s14, 0x20000
	s_addc_u32 s15, s15, 0
	s_add_u32 s16, s16, 0x20000
	s_addc_u32 s17, s17, 0
	s_waitcnt vmcnt(36)
; #define TIDX tid_fn()
; __device__ __forceinline__ void ph_rope(const Params& P) {
;     ...
;   for (size_t i = (size_t)blockIdx.x * NTHR + TIDX; i < total; i += (size_t)gridDim.x * NTHR) {
;     const int row = (int)(i / PER_ROW), it = (int)(i % PER_ROW);
;     const int f4 = it % 16, hh = (it / 16) % RET_HEADS, qk = it / (16 * RET_HEADS);
;     int isc, b, t; row_decode(row, isc, b, t);
;     const int pos = isc ? SEQ + t : t;
;     h16* pr = p + (size_t)row * NP_EV + 3 * HY_CH + qk * RETW + hh * RET_HD + f4 * 4;
;     const h16x4 t1 = *(const h16x4*)pr, t2 = *(const h16x4*)(pr + 64);
;     const float4 c = *(const float4*)(rc + (size_t)pos * 64 + f4 * 4), s = *(const float4*)(rs + (size_t)pos * 64 + f4 * 4);
;     const float sc = qk ? kscale : 1.0f;
;     h16x4 o1, o2;
;     o1[0] = (h16)(((float)t1[0] * c.x - (float)t2[0] * s.x) * sc); o2[0] = (h16)(((float)t1[0] * s.x + (float)t2[0] * c.x) * sc);
;     o1[1] = (h16)(((float)t1[1] * c.y - (float)t2[1] * s.y) * sc); o2[1] = (h16)(((float)t1[1] * s.y + (float)t2[1] * c.y) * sc);
;     o1[2] = (h16)(((float)t1[2] * c.z - (float)t2[2] * s.z) * sc); o2[2] = (h16)(((float)t1[2] * s.z + (float)t2[2] * c.z) * sc);
;     o1[3] = (h16)(((float)t1[3] * c.w - (float)t2[3] * s.w) * sc); o2[3] = (h16)(((float)t1[3] * s.w + (float)t2[3] * c.w) * sc);
;     *(h16x4*)pr = o1; *(h16x4*)(pr + 64) = o2;
;   }
	v_cvt_f32_f16_e32 v16, v80
	v_cvt_f32_f16_sdwa v17, v80 dst_sel:DWORD dst_unused:UNUSED_PAD src0_sel:WORD_1
	v_cvt_f32_f16_e32 v20, v82
	v_cvt_f32_f16_sdwa v21, v82 dst_sel:DWORD dst_unused:UNUSED_PAD src0_sel:WORD_1
	v_cvt_f32_f16_e32 v18, v81
	v_cvt_f32_f16_sdwa v19, v81 dst_sel:DWORD dst_unused:UNUSED_PAD src0_sel:WORD_1
	v_cvt_f32_f16_e32 v22, v83
	v_cvt_f32_f16_sdwa v23, v83 dst_sel:DWORD dst_unused:UNUSED_PAD src0_sel:WORD_1
	v_pk_mul_f32 v[24:25], v[16:17], v[84:85]
	v_pk_mul_f32 v[28:29], v[16:17], v[88:89]
	v_pk_mul_f32 v[26:27], v[18:19], v[86:87]
	v_pk_mul_f32 v[30:31], v[18:19], v[90:91]
	v_pk_fma_f32 v[24:25], v[20:21], v[88:89], v[24:25] neg_lo:[1,0,0] neg_hi:[1,0,0]
	v_pk_fma_f32 v[28:29], v[20:21], v[84:85], v[28:29]
	v_pk_fma_f32 v[26:27], v[22:23], v[90:91], v[26:27] neg_lo:[1,0,0] neg_hi:[1,0,0]
	v_pk_fma_f32 v[30:31], v[22:23], v[86:87], v[30:31]
	v_pk_mul_f32 v[24:25], v[24:25], v[4:5]
	v_pk_mul_f32 v[28:29], v[28:29], v[4:5]
	v_pk_mul_f32 v[26:27], v[26:27], v[4:5]
	v_pk_mul_f32 v[30:31], v[30:31], v[4:5]
	v_cvt_pk_f16_f32 v8, v24, v25
	v_cvt_pk_f16_f32 v9, v26, v27
	v_cvt_pk_f16_f32 v10, v28, v29
	v_cvt_pk_f16_f32 v11, v30, v31
	global_store_dwordx2 v1, v[8:9], s[12:13]
	global_store_dwordx2 v1, v[10:11], s[12:13] offset:128
	s_add_u32 s12, s12, 0x700000
	s_addc_u32 s13, s13, 0
	global_load_dwordx2 v[80:81], v1, s[10:11]
	global_load_dwordx2 v[82:83], v1, s[10:11] offset:128
	global_load_dwordx4 v[84:87], v2, s[14:15]
	global_load_dwordx4 v[88:91], v2, s[16:17]
	s_add_u32 s10, s10, 0x700000
	s_addc_u32 s11, s11, 0
	s_add_u32 s14, s14, 0x20000
	s_addc_u32 s15, s15, 0
	s_add_u32 s16, s16, 0x20000
	s_addc_u32 s17, s17, 0
	s_waitcnt vmcnt(38)
	v_cvt_f32_f16_e32 v16, v92
	v_cvt_f32_f16_sdwa v17, v92 dst_sel:DWORD dst_unused:UNUSED_PAD src0_sel:WORD_1
	v_cvt_f32_f16_e32 v20, v94
	v_cvt_f32_f16_sdwa v21, v94 dst_sel:DWORD dst_unused:UNUSED_PAD src0_sel:WORD_1
	v_cvt_f32_f16_e32 v18, v93
	v_cvt_f32_f16_sdwa v19, v93 dst_sel:DWORD dst_unused:UNUSED_PAD src0_sel:WORD_1
	v_cvt_f32_f16_e32 v22, v95
	v_cvt_f32_f16_sdwa v23, v95 dst_sel:DWORD dst_unused:UNUSED_PAD src0_sel:WORD_1
	v_pk_mul_f32 v[24:25], v[16:17], v[96:97]
	v_pk_mul_f32 v[28:29], v[16:17], v[100:101]
	v_pk_mul_f32 v[26:27], v[18:19], v[98:99]
	v_pk_mul_f32 v[30:31], v[18:19], v[102:103]
	v_pk_fma_f32 v[24:25], v[20:21], v[100:101], v[24:25] neg_lo:[1,0,0] neg_hi:[1,0,0]
	v_pk_fma_f32 v[28:29], v[20:21], v[96:97], v[28:29]
	v_pk_fma_f32 v[26:27], v[22:23], v[102:103], v[26:27] neg_lo:[1,0,0] neg_hi:[1,0,0]
	v_pk_fma_f32 v[30:31], v[22:23], v[98:99], v[30:31]
	v_pk_mul_f32 v[24:25], v[24:25], v[4:5]
	v_pk_mul_f32 v[28:29], v[28:29], v[4:5]
	v_pk_mul_f32 v[26:27], v[26:27], v[4:5]
	v_pk_mul_f32 v[30:31], v[30:31], v[4:5]
	v_cvt_pk_f16_f32 v12, v24, v25
	v_cvt_pk_f16_f32 v13, v26, v27
	v_cvt_pk_f16_f32 v14, v28, v29
	v_cvt_pk_f16_f32 v15, v30, v31
	global_store_dwordx2 v1, v[12:13], s[12:13]
	global_store_dwordx2 v1, v[14:15], s[12:13] offset:128
	s_add_u32 s12, s12, 0x700000
	s_addc_u32 s13, s13, 0
	global_load_dwordx2 v[92:93], v1, s[10:11]
	global_load_dwordx2 v[94:95], v1, s[10:11] offset:128
	global_load_dwordx4 v[96:99], v2, s[14:15]
	global_load_dwordx4 v[100:103], v2, s[16:17]
	s_add_u32 s10, s10, 0x700000
	s_addc_u32 s11, s11, 0
	s_add_u32 s14, s14, 0x20000
	s_addc_u32 s15, s15, 0
	s_add_u32 s16, s16, 0x20000
	s_addc_u32 s17, s17, 0
	s_waitcnt vmcnt(40)
	v_cvt_f32_f16_e32 v16, v104
	v_cvt_f32_f16_sdwa v17, v104 dst_sel:DWORD dst_unused:UNUSED_PAD src0_sel:WORD_1
	v_cvt_f32_f16_e32 v20, v106
	v_cvt_f32_f16_sdwa v21, v106 dst_sel:DWORD dst_unused:UNUSED_PAD src0_sel:WORD_1
	v_cvt_f32_f16_e32 v18, v105
	v_cvt_f32_f16_sdwa v19, v105 dst_sel:DWORD dst_unused:UNUSED_PAD src0_sel:WORD_1
	v_cvt_f32_f16_e32 v22, v107
	v_cvt_f32_f16_sdwa v23, v107 dst_sel:DWORD dst_unused:UNUSED_PAD src0_sel:WORD_1
	v_pk_mul_f32 v[24:25], v[16:17], v[108:109]
	v_pk_mul_f32 v[28:29], v[16:17], v[112:113]
	v_pk_mul_f32 v[26:27], v[18:19], v[110:111]
	v_pk_mul_f32 v[30:31], v[18:19], v[114:115]
	v_pk_fma_f32 v[24:25], v[20:21], v[112:113], v[24:25] neg_lo:[1,0,0] neg_hi:[1,0,0]
	v_pk_fma_f32 v[28:29], v[20:21], v[108:109], v[28:29]
	v_pk_fma_f32 v[26:27], v[22:23], v[114:115], v[26:27] neg_lo:[1,0,0] neg_hi:[1,0,0]
	v_pk_fma_f32 v[30:31], v[22:23], v[110:111], v[30:31]
	v_pk_mul_f32 v[24:25], v[24:25], v[4:5]
	v_pk_mul_f32 v[28:29], v[28:29], v[4:5]
	v_pk_mul_f32 v[26:27], v[26:27], v[4:5]
	v_pk_mul_f32 v[30:31], v[30:31], v[4:5]
	v_cvt_pk_f16_f32 v8, v24, v25
	v_cvt_pk_f16_f32 v9, v26, v27
	v_cvt_pk_f16_f32 v10, v28, v29
	v_cvt_pk_f16_f32 v11, v30, v31
	global_store_dwordx2 v1, v[8:9], s[12:13]
	global_store_dwordx2 v1, v[10:11], s[12:13] offset:128
	s_add_u32 s12, s12, 0x700000
	s_addc_u32 s13, s13, 0
	global_load_dwordx2 v[104:105], v1, s[10:11]
	global_load_dwordx2 v[106:107], v1, s[10:11] offset:128
	global_load_dwordx4 v[108:111], v2, s[14:15]
	global_load_dwordx4 v[112:115], v2, s[16:17]
	s_add_u32 s10, s10, 0x700000
	s_addc_u32 s11, s11, 0
	s_add_u32 s14, s14, 0x20000
	s_addc_u32 s15, s15, 0
	s_add_u32 s16, s16, 0x20000
	s_addc_u32 s17, s17, 0
	s_waitcnt vmcnt(42)
	v_cvt_f32_f16_e32 v16, v116
	v_cvt_f32_f16_sdwa v17, v116 dst_sel:DWORD dst_unused:UNUSED_PAD src0_sel:WORD_1
	v_cvt_f32_f16_e32 v20, v118
	v_cvt_f32_f16_sdwa v21, v118 dst_sel:DWORD dst_unused:UNUSED_PAD src0_sel:WORD_1
	v_cvt_f32_f16_e32 v18, v117
	v_cvt_f32_f16_sdwa v19, v117 dst_sel:DWORD dst_unused:UNUSED_PAD src0_sel:WORD_1
	v_cvt_f32_f16_e32 v22, v119
	v_cvt_f32_f16_sdwa v23, v119 dst_sel:DWORD dst_unused:UNUSED_PAD src0_sel:WORD_1
	v_pk_mul_f32 v[24:25], v[16:17], v[120:121]
	v_pk_mul_f32 v[28:29], v[16:17], v[124:125]
	v_pk_mul_f32 v[26:27], v[18:19], v[122:123]
	v_pk_mul_f32 v[30:31], v[18:19], v[126:127]
	v_pk_fma_f32 v[24:25], v[20:21], v[124:125], v[24:25] neg_lo:[1,0,0] neg_hi:[1,0,0]
	v_pk_fma_f32 v[28:29], v[20:21], v[120:121], v[28:29]
	v_pk_fma_f32 v[26:27], v[22:23], v[126:127], v[26:27] neg_lo:[1,0,0] neg_hi:[1,0,0]
	v_pk_fma_f32 v[30:31], v[22:23], v[122:123], v[30:31]
	v_pk_mul_f32 v[24:25], v[24:25], v[4:5]
	v_pk_mul_f32 v[28:29], v[28:29], v[4:5]
	v_pk_mul_f32 v[26:27], v[26:27], v[4:5]
	v_pk_mul_f32 v[30:31], v[30:31], v[4:5]
	v_cvt_pk_f16_f32 v12, v24, v25
	v_cvt_pk_f16_f32 v13, v26, v27
	v_cvt_pk_f16_f32 v14, v28, v29
	v_cvt_pk_f16_f32 v15, v30, v31
	global_store_dwordx2 v1, v[12:13], s[12:13]
	global_store_dwordx2 v1, v[14:15], s[12:13] offset:128
	s_add_u32 s12, s12, 0x700000
	s_addc_u32 s13, s13, 0
	global_load_dwordx2 v[116:117], v1, s[10:11]
	global_load_dwordx2 v[118:119], v1, s[10:11] offset:128
	global_load_dwordx4 v[120:123], v2, s[14:15]
	global_load_dwordx4 v[124:127], v2, s[16:17]
	s_add_u32 s10, s10, 0x700000
	s_addc_u32 s11, s11, 0
	s_add_u32 s14, s14, 0x20000
	s_addc_u32 s15, s15, 0
	s_add_u32 s16, s16, 0x20000
	s_addc_u32 s17, s17, 0
	s_mov_b32 s24, 1
; #define TIDX tid_fn()
; __device__ __forceinline__ void ph_rope(const Params& P) {
;     ...
;   for (size_t i = (size_t)blockIdx.x * NTHR + TIDX; i < total; i += (size_t)gridDim.x * NTHR) {
;     const int row = (int)(i / PER_ROW), it = (int)(i % PER_ROW);
;     const int f4 = it % 16, hh = (it / 16) % RET_HEADS, qk = it / (16 * RET_HEADS);
;     int isc, b, t; row_decode(row, isc, b, t);
;     const int pos = isc ? SEQ + t : t;
;     h16* pr = p + (size_t)row * NP_EV + 3 * HY_CH + qk * RETW + hh * RET_HD + f4 * 4;
;     const h16x4 t1 = *(const h16x4*)pr, t2 = *(const h16x4*)(pr + 64);
;     const float4 c = *(const float4*)(rc + (size_t)pos * 64 + f4 * 4), s = *(const float4*)(rs + (size_t)pos * 64 + f4 * 4);
;     const float sc = qk ? kscale : 1.0f;
;     h16x4 o1, o2;
;     o1[0] = (h16)(((float)t1[0] * c.x - (float)t2[0] * s.x) * sc); o2[0] = (h16)(((float)t1[0] * s.x + (float)t2[0] * c.x) * sc);
;     o1[1] = (h16)(((float)t1[1] * c.y - (float)t2[1] * s.y) * sc); o2[1] = (h16)(((float)t1[1] * s.y + (float)t2[1] * c.y) * sc);
;     o1[2] = (h16)(((float)t1[2] * c.z - (float)t2[2] * s.z) * sc); o2[2] = (h16)(((float)t1[2] * s.z + (float)t2[2] * c.z) * sc);
;     o1[3] = (h16)(((float)t1[3] * c.w - (float)t2[3] * s.w) * sc); o2[3] = (h16)(((float)t1[3] * s.w + (float)t2[3] * c.w) * sc);
;     *(h16x4*)pr = o1; *(h16x4*)(pr + 64) = o2;
;   }
.Lrope_loop:
	s_cmp_lg_u32 s24, 3
	s_cbranch_scc1 .Lrope_nr
	s_mov_b64 s[14:15], s[18:19]
	s_mov_b64 s[16:17], s[20:21]
.Lrope_nr:
	s_waitcnt vmcnt(42)
	v_cvt_f32_f16_e32 v16, v32
	v_cvt_f32_f16_sdwa v17, v32 dst_sel:DWORD dst_unused:UNUSED_PAD src0_sel:WORD_1
	v_cvt_f32_f16_e32 v20, v34
	v_cvt_f32_f16_sdwa v21, v34 dst_sel:DWORD dst_unused:UNUSED_PAD src0_sel:WORD_1
	v_cvt_f32_f16_e32 v18, v33
	v_cvt_f32_f16_sdwa v19, v33 dst_sel:DWORD dst_unused:UNUSED_PAD src0_sel:WORD_1
	v_cvt_f32_f16_e32 v22, v35
	v_cvt_f32_f16_sdwa v23, v35 dst_sel:DWORD dst_unused:UNUSED_PAD src0_sel:WORD_1
	v_pk_mul_f32 v[24:25], v[16:17], v[36:37]
	v_pk_mul_f32 v[28:29], v[16:17], v[40:41]
	v_pk_mul_f32 v[26:27], v[18:19], v[38:39]
	v_pk_mul_f32 v[30:31], v[18:19], v[42:43]
	v_pk_fma_f32 v[24:25], v[20:21], v[40:41], v[24:25] neg_lo:[1,0,0] neg_hi:[1,0,0]
	v_pk_fma_f32 v[28:29], v[20:21], v[36:37], v[28:29]
	v_pk_fma_f32 v[26:27], v[22:23], v[42:43], v[26:27] neg_lo:[1,0,0] neg_hi:[1,0,0]
	v_pk_fma_f32 v[30:31], v[22:23], v[38:39], v[30:31]
	v_pk_mul_f32 v[24:25], v[24:25], v[4:5]
	v_pk_mul_f32 v[28:29], v[28:29], v[4:5]
	v_pk_mul_f32 v[26:27], v[26:27], v[4:5]
	v_pk_mul_f32 v[30:31], v[30:31], v[4:5]
	v_cvt_pk_f16_f32 v8, v24, v25
	v_cvt_pk_f16_f32 v9, v26, v27
	v_cvt_pk_f16_f32 v10, v28, v29
	v_cvt_pk_f16_f32 v11, v30, v31
	global_store_dwordx2 v1, v[8:9], s[12:13]
	global_store_dwordx2 v1, v[10:11], s[12:13] offset:128
	s_add_u32 s12, s12, 0x700000
	s_addc_u32 s13, s13, 0
	global_load_dwordx2 v[32:33], v1, s[10:11]
	global_load_dwordx2 v[34:35], v1, s[10:11] offset:128
	global_load_dwordx4 v[36:39], v2, s[14:15]
	global_load_dwordx4 v[40:43], v2, s[16:17]
	s_add_u32 s10, s10, 0x700000
	s_addc_u32 s11, s11, 0
	s_add_u32 s14, s14, 0x20000
	s_addc_u32 s15, s15, 0
	s_add_u32 s16, s16, 0x20000
	s_addc_u32 s17, s17, 0
	s_waitcnt vmcnt(42)
	v_cvt_f32_f16_e32 v16, v44
	v_cvt_f32_f16_sdwa v17, v44 dst_sel:DWORD dst_unused:UNUSED_PAD src0_sel:WORD_1
	v_cvt_f32_f16_e32 v20, v46
	v_cvt_f32_f16_sdwa v21, v46 dst_sel:DWORD dst_unused:UNUSED_PAD src0_sel:WORD_1
	v_cvt_f32_f16_e32 v18, v45
	v_cvt_f32_f16_sdwa v19, v45 dst_sel:DWORD dst_unused:UNUSED_PAD src0_sel:WORD_1
	v_cvt_f32_f16_e32 v22, v47
	v_cvt_f32_f16_sdwa v23, v47 dst_sel:DWORD dst_unused:UNUSED_PAD src0_sel:WORD_1
	v_pk_mul_f32 v[24:25], v[16:17], v[48:49]
	v_pk_mul_f32 v[28:29], v[16:17], v[52:53]
	v_pk_mul_f32 v[26:27], v[18:19], v[50:51]
	v_pk_mul_f32 v[30:31], v[18:19], v[54:55]
	v_pk_fma_f32 v[24:25], v[20:21], v[52:53], v[24:25] neg_lo:[1,0,0] neg_hi:[1,0,0]
	v_pk_fma_f32 v[28:29], v[20:21], v[48:49], v[28:29]
	v_pk_fma_f32 v[26:27], v[22:23], v[54:55], v[26:27] neg_lo:[1,0,0] neg_hi:[1,0,0]
	v_pk_fma_f32 v[30:31], v[22:23], v[50:51], v[30:31]
	v_pk_mul_f32 v[24:25], v[24:25], v[4:5]
	v_pk_mul_f32 v[28:29], v[28:29], v[4:5]
	v_pk_mul_f32 v[26:27], v[26:27], v[4:5]
	v_pk_mul_f32 v[30:31], v[30:31], v[4:5]
	v_cvt_pk_f16_f32 v12, v24, v25
	v_cvt_pk_f16_f32 v13, v26, v27
	v_cvt_pk_f16_f32 v14, v28, v29
	v_cvt_pk_f16_f32 v15, v30, v31
	global_store_dwordx2 v1, v[12:13], s[12:13]
	global_store_dwordx2 v1, v[14:15], s[12:13] offset:128
	s_add_u32 s12, s12, 0x700000
	s_addc_u32 s13, s13, 0
	global_load_dwordx2 v[44:45], v1, s[10:11]
	global_load_dwordx2 v[46:47], v1, s[10:11] offset:128
	global_load_dwordx4 v[48:51], v2, s[14:15]
	global_load_dwordx4 v[52:55], v2, s[16:17]
	s_add_u32 s10, s10, 0x700000
	s_addc_u32 s11, s11, 0
	s_add_u32 s14, s14, 0x20000
	s_addc_u32 s15, s15, 0
	s_add_u32 s16, s16, 0x20000
	s_addc_u32 s17, s17, 0
	s_waitcnt vmcnt(42)
	v_cvt_f32_f16_e32 v16, v56
	v_cvt_f32_f16_sdwa v17, v56 dst_sel:DWORD dst_unused:UNUSED_PAD src0_sel:WORD_1
	v_cvt_f32_f16_e32 v20, v58
	v_cvt_f32_f16_sdwa v21, v58 dst_sel:DWORD dst_unused:UNUSED_PAD src0_sel:WORD_1
	v_cvt_f32_f16_e32 v18, v57
	v_cvt_f32_f16_sdwa v19, v57 dst_sel:DWORD dst_unused:UNUSED_PAD src0_sel:WORD_1
	v_cvt_f32_f16_e32 v22, v59
	v_cvt_f32_f16_sdwa v23, v59 dst_sel:DWORD dst_unused:UNUSED_PAD src0_sel:WORD_1
	v_pk_mul_f32 v[24:25], v[16:17], v[60:61]
	v_pk_mul_f32 v[28:29], v[16:17], v[64:65]
	v_pk_mul_f32 v[26:27], v[18:19], v[62:63]
	v_pk_mul_f32 v[30:31], v[18:19], v[66:67]
	v_pk_fma_f32 v[24:25], v[20:21], v[64:65], v[24:25] neg_lo:[1,0,0] neg_hi:[1,0,0]
	v_pk_fma_f32 v[28:29], v[20:21], v[60:61], v[28:29]
	v_pk_fma_f32 v[26:27], v[22:23], v[66:67], v[26:27] neg_lo:[1,0,0] neg_hi:[1,0,0]
	v_pk_fma_f32 v[30:31], v[22:23], v[62:63], v[30:31]
	v_pk_mul_f32 v[24:25], v[24:25], v[4:5]
	v_pk_mul_f32 v[28:29], v[28:29], v[4:5]
	v_pk_mul_f32 v[26:27], v[26:27], v[4:5]
	v_pk_mul_f32 v[30:31], v[30:31], v[4:5]
	v_cvt_pk_f16_f32 v8, v24, v25
	v_cvt_pk_f16_f32 v9, v26, v27
	v_cvt_pk_f16_f32 v10, v28, v29
	v_cvt_pk_f16_f32 v11, v30, v31
	global_store_dwordx2 v1, v[8:9], s[12:13]
	global_store_dwordx2 v1, v[10:11], s[12:13] offset:128
	s_add_u32 s12, s12, 0x700000
	s_addc_u32 s13, s13, 0
	global_load_dwordx2 v[56:57], v1, s[10:11]
	global_load_dwordx2 v[58:59], v1, s[10:11] offset:128
	global_load_dwordx4 v[60:63], v2, s[14:15]
	global_load_dwordx4 v[64:67], v2, s[16:17]
	s_add_u32 s10, s10, 0x700000
	s_addc_u32 s11, s11, 0
	s_add_u32 s14, s14, 0x20000
	s_addc_u32 s15, s15, 0
	s_add_u32 s16, s16, 0x20000
	s_addc_u32 s17, s17, 0
	s_waitcnt vmcnt(42)
; #define TIDX tid_fn()
; __device__ __forceinline__ void ph_rope(const Params& P) {
;     ...
;   for (size_t i = (size_t)blockIdx.x * NTHR + TIDX; i < total; i += (size_t)gridDim.x * NTHR) {
;     const int row = (int)(i / PER_ROW), it = (int)(i % PER_ROW);
;     const int f4 = it % 16, hh = (it / 16) % RET_HEADS, qk = it / (16 * RET_HEADS);
;     int isc, b, t; row_decode(row, isc, b, t);
;     const int pos = isc ? SEQ + t : t;
;     h16* pr = p + (size_t)row * NP_EV + 3 * HY_CH + qk * RETW + hh * RET_HD + f4 * 4;
;     const h16x4 t1 = *(const h16x4*)pr, t2 = *(const h16x4*)(pr + 64);
;     const float4 c = *(const float4*)(rc + (size_t)pos * 64 + f4 * 4), s = *(const float4*)(rs + (size_t)pos * 64 + f4 * 4);
;     const float sc = qk ? kscale : 1.0f;
;     h16x4 o1, o2;
;     o1[0] = (h16)(((float)t1[0] * c.x - (float)t2[0] * s.x) * sc); o2[0] = (h16)(((float)t1[0] * s.x + (float)t2[0] * c.x) * sc);
;     o1[1] = (h16)(((float)t1[1] * c.y - (float)t2[1] * s.y) * sc); o2[1] = (h16)(((float)t1[1] * s.y + (float)t2[1] * c.y) * sc);
;     o1[2] = (h16)(((float)t1[2] * c.z - (float)t2[2] * s.z) * sc); o2[2] = (h16)(((float)t1[2] * s.z + (float)t2[2] * c.z) * sc);
;     o1[3] = (h16)(((float)t1[3] * c.w - (float)t2[3] * s.w) * sc); o2[3] = (h16)(((float)t1[3] * s.w + (float)t2[3] * c.w) * sc);
;     *(h16x4*)pr = o1; *(h16x4*)(pr + 64) = o2;
;   }
	v_cvt_f32_f16_e32 v16, v68
	v_cvt_f32_f16_sdwa v17, v68 dst_sel:DWORD dst_unused:UNUSED_PAD src0_sel:WORD_1
	v_cvt_f32_f16_e32 v20, v70
	v_cvt_f32_f16_sdwa v21, v70 dst_sel:DWORD dst_unused:UNUSED_PAD src0_sel:WORD_1
	v_cvt_f32_f16_e32 v18, v69
	v_cvt_f32_f16_sdwa v19, v69 dst_sel:DWORD dst_unused:UNUSED_PAD src0_sel:WORD_1
	v_cvt_f32_f16_e32 v22, v71
	v_cvt_f32_f16_sdwa v23, v71 dst_sel:DWORD dst_unused:UNUSED_PAD src0_sel:WORD_1
	v_pk_mul_f32 v[24:25], v[16:17], v[72:73]
	v_pk_mul_f32 v[28:29], v[16:17], v[76:77]
	v_pk_mul_f32 v[26:27], v[18:19], v[74:75]
	v_pk_mul_f32 v[30:31], v[18:19], v[78:79]
	v_pk_fma_f32 v[24:25], v[20:21], v[76:77], v[24:25] neg_lo:[1,0,0] neg_hi:[1,0,0]
	v_pk_fma_f32 v[28:29], v[20:21], v[72:73], v[28:29]
	v_pk_fma_f32 v[26:27], v[22:23], v[78:79], v[26:27] neg_lo:[1,0,0] neg_hi:[1,0,0]
	v_pk_fma_f32 v[30:31], v[22:23], v[74:75], v[30:31]
	v_pk_mul_f32 v[24:25], v[24:25], v[4:5]
	v_pk_mul_f32 v[28:29], v[28:29], v[4:5]
	v_pk_mul_f32 v[26:27], v[26:27], v[4:5]
	v_pk_mul_f32 v[30:31], v[30:31], v[4:5]
	v_cvt_pk_f16_f32 v12, v24, v25
	v_cvt_pk_f16_f32 v13, v26, v27
	v_cvt_pk_f16_f32 v14, v28, v29
	v_cvt_pk_f16_f32 v15, v30, v31
	global_store_dwordx2 v1, v[12:13], s[12:13]
	global_store_dwordx2 v1, v[14:15], s[12:13] offset:128
	s_add_u32 s12, s12, 0x700000
	s_addc_u32 s13, s13, 0
	global_load_dwordx2 v[68:69], v1, s[10:11]
	global_load_dwordx2 v[70:71], v1, s[10:11] offset:128
	global_load_dwordx4 v[72:75], v2, s[14:15]
	global_load_dwordx4 v[76:79], v2, s[16:17]
	s_add_u32 s10, s10, 0x700000
	s_addc_u32 s11, s11, 0
	s_add_u32 s14, s14, 0x20000
	s_addc_u32 s15, s15, 0
	s_add_u32 s16, s16, 0x20000
	s_addc_u32 s17, s17, 0
	s_waitcnt vmcnt(42)
	v_cvt_f32_f16_e32 v16, v80
	v_cvt_f32_f16_sdwa v17, v80 dst_sel:DWORD dst_unused:UNUSED_PAD src0_sel:WORD_1
	v_cvt_f32_f16_e32 v20, v82
	v_cvt_f32_f16_sdwa v21, v82 dst_sel:DWORD dst_unused:UNUSED_PAD src0_sel:WORD_1
	v_cvt_f32_f16_e32 v18, v81
	v_cvt_f32_f16_sdwa v19, v81 dst_sel:DWORD dst_unused:UNUSED_PAD src0_sel:WORD_1
	v_cvt_f32_f16_e32 v22, v83
	v_cvt_f32_f16_sdwa v23, v83 dst_sel:DWORD dst_unused:UNUSED_PAD src0_sel:WORD_1
	v_pk_mul_f32 v[24:25], v[16:17], v[84:85]
	v_pk_mul_f32 v[28:29], v[16:17], v[88:89]
	v_pk_mul_f32 v[26:27], v[18:19], v[86:87]
	v_pk_mul_f32 v[30:31], v[18:19], v[90:91]
	v_pk_fma_f32 v[24:25], v[20:21], v[88:89], v[24:25] neg_lo:[1,0,0] neg_hi:[1,0,0]
	v_pk_fma_f32 v[28:29], v[20:21], v[84:85], v[28:29]
	v_pk_fma_f32 v[26:27], v[22:23], v[90:91], v[26:27] neg_lo:[1,0,0] neg_hi:[1,0,0]
	v_pk_fma_f32 v[30:31], v[22:23], v[86:87], v[30:31]
	v_pk_mul_f32 v[24:25], v[24:25], v[4:5]
	v_pk_mul_f32 v[28:29], v[28:29], v[4:5]
	v_pk_mul_f32 v[26:27], v[26:27], v[4:5]
	v_pk_mul_f32 v[30:31], v[30:31], v[4:5]
	v_cvt_pk_f16_f32 v8, v24, v25
	v_cvt_pk_f16_f32 v9, v26, v27
	v_cvt_pk_f16_f32 v10, v28, v29
	v_cvt_pk_f16_f32 v11, v30, v31
	global_store_dwordx2 v1, v[8:9], s[12:13]
	global_store_dwordx2 v1, v[10:11], s[12:13] offset:128
	s_add_u32 s12, s12, 0x700000
	s_addc_u32 s13, s13, 0
	global_load_dwordx2 v[80:81], v1, s[10:11]
	global_load_dwordx2 v[82:83], v1, s[10:11] offset:128
	global_load_dwordx4 v[84:87], v2, s[14:15]
	global_load_dwordx4 v[88:91], v2, s[16:17]
	s_add_u32 s10, s10, 0x700000
	s_addc_u32 s11, s11, 0
	s_add_u32 s14, s14, 0x20000
	s_addc_u32 s15, s15, 0
	s_add_u32 s16, s16, 0x20000
	s_addc_u32 s17, s17, 0
	s_waitcnt vmcnt(42)
	v_cvt_f32_f16_e32 v16, v92
	v_cvt_f32_f16_sdwa v17, v92 dst_sel:DWORD dst_unused:UNUSED_PAD src0_sel:WORD_1
	v_cvt_f32_f16_e32 v20, v94
	v_cvt_f32_f16_sdwa v21, v94 dst_sel:DWORD dst_unused:UNUSED_PAD src0_sel:WORD_1
	v_cvt_f32_f16_e32 v18, v93
	v_cvt_f32_f16_sdwa v19, v93 dst_sel:DWORD dst_unused:UNUSED_PAD src0_sel:WORD_1
	v_cvt_f32_f16_e32 v22, v95
	v_cvt_f32_f16_sdwa v23, v95 dst_sel:DWORD dst_unused:UNUSED_PAD src0_sel:WORD_1
	v_pk_mul_f32 v[24:25], v[16:17], v[96:97]
	v_pk_mul_f32 v[28:29], v[16:17], v[100:101]
	v_pk_mul_f32 v[26:27], v[18:19], v[98:99]
	v_pk_mul_f32 v[30:31], v[18:19], v[102:103]
	v_pk_fma_f32 v[24:25], v[20:21], v[100:101], v[24:25] neg_lo:[1,0,0] neg_hi:[1,0,0]
	v_pk_fma_f32 v[28:29], v[20:21], v[96:97], v[28:29]
	v_pk_fma_f32 v[26:27], v[22:23], v[102:103], v[26:27] neg_lo:[1,0,0] neg_hi:[1,0,0]
	v_pk_fma_f32 v[30:31], v[22:23], v[98:99], v[30:31]
	v_pk_mul_f32 v[24:25], v[24:25], v[4:5]
	v_pk_mul_f32 v[28:29], v[28:29], v[4:5]
	v_pk_mul_f32 v[26:27], v[26:27], v[4:5]
	v_pk_mul_f32 v[30:31], v[30:31], v[4:5]
	v_cvt_pk_f16_f32 v12, v24, v25
	v_cvt_pk_f16_f32 v13, v26, v27
	v_cvt_pk_f16_f32 v14, v28, v29
	v_cvt_pk_f16_f32 v15, v30, v31
	global_store_dwordx2 v1, v[12:13], s[12:13]
	global_store_dwordx2 v1, v[14:15], s[12:13] offset:128
	s_add_u32 s12, s12, 0x700000
	s_addc_u32 s13, s13, 0
	global_load_dwordx2 v[92:93], v1, s[10:11]
	global_load_dwordx2 v[94:95], v1, s[10:11] offset:128
	global_load_dwordx4 v[96:99], v2, s[14:15]
	global_load_dwordx4 v[100:103], v2, s[16:17]
	s_add_u32 s10, s10, 0x700000
	s_addc_u32 s11, s11, 0
	s_add_u32 s14, s14, 0x20000
	s_addc_u32 s15, s15, 0
	s_add_u32 s16, s16, 0x20000
	s_addc_u32 s17, s17, 0
	s_waitcnt vmcnt(42)
; #define TIDX tid_fn()
; __device__ __forceinline__ void ph_rope(const Params& P) {
;     ...
;   for (size_t i = (size_t)blockIdx.x * NTHR + TIDX; i < total; i += (size_t)gridDim.x * NTHR) {
;     const int row = (int)(i / PER_ROW), it = (int)(i % PER_ROW);
;     const int f4 = it % 16, hh = (it / 16) % RET_HEADS, qk = it / (16 * RET_HEADS);
;     int isc, b, t; row_decode(row, isc, b, t);
;     const int pos = isc ? SEQ + t : t;
;     h16* pr = p + (size_t)row * NP_EV + 3 * HY_CH + qk * RETW + hh * RET_HD + f4 * 4;
;     const h16x4 t1 = *(const h16x4*)pr, t2 = *(const h16x4*)(pr + 64);
;     const float4 c = *(const float4*)(rc + (size_t)pos * 64 + f4 * 4), s = *(const float4*)(rs + (size_t)pos * 64 + f4 * 4);
;     const float sc = qk ? kscale : 1.0f;
;     h16x4 o1, o2;
;     o1[0] = (h16)(((float)t1[0] * c.x - (float)t2[0] * s.x) * sc); o2[0] = (h16)(((float)t1[0] * s.x + (float)t2[0] * c.x) * sc);
;     o1[1] = (h16)(((float)t1[1] * c.y - (float)t2[1] * s.y) * sc); o2[1] = (h16)(((float)t1[1] * s.y + (float)t2[1] * c.y) * sc);
;     o1[2] = (h16)(((float)t1[2] * c.z - (float)t2[2] * s.z) * sc); o2[2] = (h16)(((float)t1[2] * s.z + (float)t2[2] * c.z) * sc);
;     o1[3] = (h16)(((float)t1[3] * c.w - (float)t2[3] * s.w) * sc); o2[3] = (h16)(((float)t1[3] * s.w + (float)t2[3] * c.w) * sc);
;     *(h16x4*)pr = o1; *(h16x4*)(pr + 64) = o2;
;   }
	v_cvt_f32_f16_e32 v16, v104
	v_cvt_f32_f16_sdwa v17, v104 dst_sel:DWORD dst_unused:UNUSED_PAD src0_sel:WORD_1
	v_cvt_f32_f16_e32 v20, v106
	v_cvt_f32_f16_sdwa v21, v106 dst_sel:DWORD dst_unused:UNUSED_PAD src0_sel:WORD_1
	v_cvt_f32_f16_e32 v18, v105
	v_cvt_f32_f16_sdwa v19, v105 dst_sel:DWORD dst_unused:UNUSED_PAD src0_sel:WORD_1
	v_cvt_f32_f16_e32 v22, v107
	v_cvt_f32_f16_sdwa v23, v107 dst_sel:DWORD dst_unused:UNUSED_PAD src0_sel:WORD_1
	v_pk_mul_f32 v[24:25], v[16:17], v[108:109]
	v_pk_mul_f32 v[28:29], v[16:17], v[112:113]
	v_pk_mul_f32 v[26:27], v[18:19], v[110:111]
	v_pk_mul_f32 v[30:31], v[18:19], v[114:115]
	v_pk_fma_f32 v[24:25], v[20:21], v[112:113], v[24:25] neg_lo:[1,0,0] neg_hi:[1,0,0]
	v_pk_fma_f32 v[28:29], v[20:21], v[108:109], v[28:29]
	v_pk_fma_f32 v[26:27], v[22:23], v[114:115], v[26:27] neg_lo:[1,0,0] neg_hi:[1,0,0]
	v_pk_fma_f32 v[30:31], v[22:23], v[110:111], v[30:31]
	v_pk_mul_f32 v[24:25], v[24:25], v[4:5]
	v_pk_mul_f32 v[28:29], v[28:29], v[4:5]
	v_pk_mul_f32 v[26:27], v[26:27], v[4:5]
	v_pk_mul_f32 v[30:31], v[30:31], v[4:5]
	v_cvt_pk_f16_f32 v8, v24, v25
	v_cvt_pk_f16_f32 v9, v26, v27
	v_cvt_pk_f16_f32 v10, v28, v29
	v_cvt_pk_f16_f32 v11, v30, v31
	global_store_dwordx2 v1, v[8:9], s[12:13]
	global_store_dwordx2 v1, v[10:11], s[12:13] offset:128
	s_add_u32 s12, s12, 0x700000
	s_addc_u32 s13, s13, 0
	global_load_dwordx2 v[104:105], v1, s[10:11]
	global_load_dwordx2 v[106:107], v1, s[10:11] offset:128
	global_load_dwordx4 v[108:111], v2, s[14:15]
	global_load_dwordx4 v[112:115], v2, s[16:17]
	s_add_u32 s10, s10, 0x700000
	s_addc_u32 s11, s11, 0
	s_add_u32 s14, s14, 0x20000
	s_addc_u32 s15, s15, 0
	s_add_u32 s16, s16, 0x20000
	s_addc_u32 s17, s17, 0
	s_waitcnt vmcnt(42)
	v_cvt_f32_f16_e32 v16, v116
	v_cvt_f32_f16_sdwa v17, v116 dst_sel:DWORD dst_unused:UNUSED_PAD src0_sel:WORD_1
	v_cvt_f32_f16_e32 v20, v118
	v_cvt_f32_f16_sdwa v21, v118 dst_sel:DWORD dst_unused:UNUSED_PAD src0_sel:WORD_1
	v_cvt_f32_f16_e32 v18, v117
	v_cvt_f32_f16_sdwa v19, v117 dst_sel:DWORD dst_unused:UNUSED_PAD src0_sel:WORD_1
	v_cvt_f32_f16_e32 v22, v119
	v_cvt_f32_f16_sdwa v23, v119 dst_sel:DWORD dst_unused:UNUSED_PAD src0_sel:WORD_1
	v_pk_mul_f32 v[24:25], v[16:17], v[120:121]
	v_pk_mul_f32 v[28:29], v[16:17], v[124:125]
	v_pk_mul_f32 v[26:27], v[18:19], v[122:123]
	v_pk_mul_f32 v[30:31], v[18:19], v[126:127]
	v_pk_fma_f32 v[24:25], v[20:21], v[124:125], v[24:25] neg_lo:[1,0,0] neg_hi:[1,0,0]
	v_pk_fma_f32 v[28:29], v[20:21], v[120:121], v[28:29]
	v_pk_fma_f32 v[26:27], v[22:23], v[126:127], v[26:27] neg_lo:[1,0,0] neg_hi:[1,0,0]
	v_pk_fma_f32 v[30:31], v[22:23], v[122:123], v[30:31]
	v_pk_mul_f32 v[24:25], v[24:25], v[4:5]
	v_pk_mul_f32 v[28:29], v[28:29], v[4:5]
	v_pk_mul_f32 v[26:27], v[26:27], v[4:5]
	v_pk_mul_f32 v[30:31], v[30:31], v[4:5]
	v_cvt_pk_f16_f32 v12, v24, v25
	v_cvt_pk_f16_f32 v13, v26, v27
	v_cvt_pk_f16_f32 v14, v28, v29
	v_cvt_pk_f16_f32 v15, v30, v31
	global_store_dwordx2 v1, v[12:13], s[12:13]
	global_store_dwordx2 v1, v[14:15], s[12:13] offset:128
	s_add_u32 s12, s12, 0x700000
	s_addc_u32 s13, s13, 0
	global_load_dwordx2 v[116:117], v1, s[10:11]
	global_load_dwordx2 v[118:119], v1, s[10:11] offset:128
	global_load_dwordx4 v[120:123], v2, s[14:15]
	global_load_dwordx4 v[124:127], v2, s[16:17]
	s_add_u32 s10, s10, 0x700000
	s_addc_u32 s11, s11, 0
	s_add_u32 s14, s14, 0x20000
	s_addc_u32 s15, s15, 0
	s_add_u32 s16, s16, 0x20000
	s_addc_u32 s17, s17, 0
	s_add_u32 s24, s24, 1
	s_cmp_lt_u32 s24, 7
	s_cbranch_scc1 .Lrope_loop
	s_waitcnt vmcnt(0)
	v_cvt_f32_f16_e32 v16, v32
	v_cvt_f32_f16_sdwa v17, v32 dst_sel:DWORD dst_unused:UNUSED_PAD src0_sel:WORD_1
	v_cvt_f32_f16_e32 v20, v34
	v_cvt_f32_f16_sdwa v21, v34 dst_sel:DWORD dst_unused:UNUSED_PAD src0_sel:WORD_1
	v_cvt_f32_f16_e32 v18, v33
	v_cvt_f32_f16_sdwa v19, v33 dst_sel:DWORD dst_unused:UNUSED_PAD src0_sel:WORD_1
	v_cvt_f32_f16_e32 v22, v35
	v_cvt_f32_f16_sdwa v23, v35 dst_sel:DWORD dst_unused:UNUSED_PAD src0_sel:WORD_1
	v_pk_mul_f32 v[24:25], v[16:17], v[36:37]
	v_pk_mul_f32 v[28:29], v[16:17], v[40:41]
	v_pk_mul_f32 v[26:27], v[18:19], v[38:39]
	v_pk_mul_f32 v[30:31], v[18:19], v[42:43]
	v_pk_fma_f32 v[24:25], v[20:21], v[40:41], v[24:25] neg_lo:[1,0,0] neg_hi:[1,0,0]
	v_pk_fma_f32 v[28:29], v[20:21], v[36:37], v[28:29]
	v_pk_fma_f32 v[26:27], v[22:23], v[42:43], v[26:27] neg_lo:[1,0,0] neg_hi:[1,0,0]
	v_pk_fma_f32 v[30:31], v[22:23], v[38:39], v[30:31]
	v_pk_mul_f32 v[24:25], v[24:25], v[4:5]
	v_pk_mul_f32 v[28:29], v[28:29], v[4:5]
	v_pk_mul_f32 v[26:27], v[26:27], v[4:5]
	v_pk_mul_f32 v[30:31], v[30:31], v[4:5]
	v_cvt_pk_f16_f32 v8, v24, v25
	v_cvt_pk_f16_f32 v9, v26, v27
	v_cvt_pk_f16_f32 v10, v28, v29
	v_cvt_pk_f16_f32 v11, v30, v31
	global_store_dwordx2 v1, v[8:9], s[12:13]
	global_store_dwordx2 v1, v[10:11], s[12:13] offset:128
	s_add_u32 s12, s12, 0x700000
	s_addc_u32 s13, s13, 0
	v_cvt_f32_f16_e32 v16, v44
	v_cvt_f32_f16_sdwa v17, v44 dst_sel:DWORD dst_unused:UNUSED_PAD src0_sel:WORD_1
	v_cvt_f32_f16_e32 v20, v46
	v_cvt_f32_f16_sdwa v21, v46 dst_sel:DWORD dst_unused:UNUSED_PAD src0_sel:WORD_1
	v_cvt_f32_f16_e32 v18, v45
	v_cvt_f32_f16_sdwa v19, v45 dst_sel:DWORD dst_unused:UNUSED_PAD src0_sel:WORD_1
	v_cvt_f32_f16_e32 v22, v47
	v_cvt_f32_f16_sdwa v23, v47 dst_sel:DWORD dst_unused:UNUSED_PAD src0_sel:WORD_1
	v_pk_mul_f32 v[24:25], v[16:17], v[48:49]
	v_pk_mul_f32 v[28:29], v[16:17], v[52:53]
	v_pk_mul_f32 v[26:27], v[18:19], v[50:51]
	v_pk_mul_f32 v[30:31], v[18:19], v[54:55]
	v_pk_fma_f32 v[24:25], v[20:21], v[52:53], v[24:25] neg_lo:[1,0,0] neg_hi:[1,0,0]
	v_pk_fma_f32 v[28:29], v[20:21], v[48:49], v[28:29]
	v_pk_fma_f32 v[26:27], v[22:23], v[54:55], v[26:27] neg_lo:[1,0,0] neg_hi:[1,0,0]
; #define TIDX tid_fn()
; __device__ __forceinline__ void ph_rope(const Params& P) {
;     ...
;   for (size_t i = (size_t)blockIdx.x * NTHR + TIDX; i < total; i += (size_t)gridDim.x * NTHR) {
;     const int row = (int)(i / PER_ROW), it = (int)(i % PER_ROW);
;     const int f4 = it % 16, hh = (it / 16) % RET_HEADS, qk = it / (16 * RET_HEADS);
;     int isc, b, t; row_decode(row, isc, b, t);
;     const int pos = isc ? SEQ + t : t;
;     h16* pr = p + (size_t)row * NP_EV + 3 * HY_CH + qk * RETW + hh * RET_HD + f4 * 4;
;     const h16x4 t1 = *(const h16x4*)pr, t2 = *(const h16x4*)(pr + 64);
;     const float4 c = *(const float4*)(rc + (size_t)pos * 64 + f4 * 4), s = *(const float4*)(rs + (size_t)pos * 64 + f4 * 4);
;     const float sc = qk ? kscale : 1.0f;
;     h16x4 o1, o2;
;     o1[0] = (h16)(((float)t1[0] * c.x - (float)t2[0] * s.x) * sc); o2[0] = (h16)(((float)t1[0] * s.x + (float)t2[0] * c.x) * sc);
;     o1[1] = (h16)(((float)t1[1] * c.y - (float)t2[1] * s.y) * sc); o2[1] = (h16)(((float)t1[1] * s.y + (float)t2[1] * c.y) * sc);
;     o1[2] = (h16)(((float)t1[2] * c.z - (float)t2[2] * s.z) * sc); o2[2] = (h16)(((float)t1[2] * s.z + (float)t2[2] * c.z) * sc);
;     o1[3] = (h16)(((float)t1[3] * c.w - (float)t2[3] * s.w) * sc); o2[3] = (h16)(((float)t1[3] * s.w + (float)t2[3] * c.w) * sc);
;     *(h16x4*)pr = o1; *(h16x4*)(pr + 64) = o2;
;   }
	v_pk_fma_f32 v[30:31], v[22:23], v[50:51], v[30:31]
	v_pk_mul_f32 v[24:25], v[24:25], v[4:5]
	v_pk_mul_f32 v[28:29], v[28:29], v[4:5]
	v_pk_mul_f32 v[26:27], v[26:27], v[4:5]
	v_pk_mul_f32 v[30:31], v[30:31], v[4:5]
	v_cvt_pk_f16_f32 v12, v24, v25
	v_cvt_pk_f16_f32 v13, v26, v27
	v_cvt_pk_f16_f32 v14, v28, v29
	v_cvt_pk_f16_f32 v15, v30, v31
	global_store_dwordx2 v1, v[12:13], s[12:13]
	global_store_dwordx2 v1, v[14:15], s[12:13] offset:128
	s_add_u32 s12, s12, 0x700000
	s_addc_u32 s13, s13, 0
	v_cvt_f32_f16_e32 v16, v56
	v_cvt_f32_f16_sdwa v17, v56 dst_sel:DWORD dst_unused:UNUSED_PAD src0_sel:WORD_1
	v_cvt_f32_f16_e32 v20, v58
	v_cvt_f32_f16_sdwa v21, v58 dst_sel:DWORD dst_unused:UNUSED_PAD src0_sel:WORD_1
	v_cvt_f32_f16_e32 v18, v57
	v_cvt_f32_f16_sdwa v19, v57 dst_sel:DWORD dst_unused:UNUSED_PAD src0_sel:WORD_1
	v_cvt_f32_f16_e32 v22, v59
	v_cvt_f32_f16_sdwa v23, v59 dst_sel:DWORD dst_unused:UNUSED_PAD src0_sel:WORD_1
	v_pk_mul_f32 v[24:25], v[16:17], v[60:61]
	v_pk_mul_f32 v[28:29], v[16:17], v[64:65]
	v_pk_mul_f32 v[26:27], v[18:19], v[62:63]
	v_pk_mul_f32 v[30:31], v[18:19], v[66:67]
	v_pk_fma_f32 v[24:25], v[20:21], v[64:65], v[24:25] neg_lo:[1,0,0] neg_hi:[1,0,0]
	v_pk_fma_f32 v[28:29], v[20:21], v[60:61], v[28:29]
	v_pk_fma_f32 v[26:27], v[22:23], v[66:67], v[26:27] neg_lo:[1,0,0] neg_hi:[1,0,0]
	v_pk_fma_f32 v[30:31], v[22:23], v[62:63], v[30:31]
	v_pk_mul_f32 v[24:25], v[24:25], v[4:5]
	v_pk_mul_f32 v[28:29], v[28:29], v[4:5]
	v_pk_mul_f32 v[26:27], v[26:27], v[4:5]
	v_pk_mul_f32 v[30:31], v[30:31], v[4:5]
	v_cvt_pk_f16_f32 v8, v24, v25
	v_cvt_pk_f16_f32 v9, v26, v27
	v_cvt_pk_f16_f32 v10, v28, v29
	v_cvt_pk_f16_f32 v11, v30, v31
	global_store_dwordx2 v1, v[8:9], s[12:13]
	global_store_dwordx2 v1, v[10:11], s[12:13] offset:128
	s_add_u32 s12, s12, 0x700000
	s_addc_u32 s13, s13, 0
	v_cvt_f32_f16_e32 v16, v68
	v_cvt_f32_f16_sdwa v17, v68 dst_sel:DWORD dst_unused:UNUSED_PAD src0_sel:WORD_1
	v_cvt_f32_f16_e32 v20, v70
	v_cvt_f32_f16_sdwa v21, v70 dst_sel:DWORD dst_unused:UNUSED_PAD src0_sel:WORD_1
	v_cvt_f32_f16_e32 v18, v69
	v_cvt_f32_f16_sdwa v19, v69 dst_sel:DWORD dst_unused:UNUSED_PAD src0_sel:WORD_1
	v_cvt_f32_f16_e32 v22, v71
	v_cvt_f32_f16_sdwa v23, v71 dst_sel:DWORD dst_unused:UNUSED_PAD src0_sel:WORD_1
	v_pk_mul_f32 v[24:25], v[16:17], v[72:73]
	v_pk_mul_f32 v[28:29], v[16:17], v[76:77]
	v_pk_mul_f32 v[26:27], v[18:19], v[74:75]
	v_pk_mul_f32 v[30:31], v[18:19], v[78:79]
	v_pk_fma_f32 v[24:25], v[20:21], v[76:77], v[24:25] neg_lo:[1,0,0] neg_hi:[1,0,0]
	v_pk_fma_f32 v[28:29], v[20:21], v[72:73], v[28:29]
	v_pk_fma_f32 v[26:27], v[22:23], v[78:79], v[26:27] neg_lo:[1,0,0] neg_hi:[1,0,0]
	v_pk_fma_f32 v[30:31], v[22:23], v[74:75], v[30:31]
	v_pk_mul_f32 v[24:25], v[24:25], v[4:5]
	v_pk_mul_f32 v[28:29], v[28:29], v[4:5]
	v_pk_mul_f32 v[26:27], v[26:27], v[4:5]
	v_pk_mul_f32 v[30:31], v[30:31], v[4:5]
	v_cvt_pk_f16_f32 v12, v24, v25
	v_cvt_pk_f16_f32 v13, v26, v27
	v_cvt_pk_f16_f32 v14, v28, v29
	v_cvt_pk_f16_f32 v15, v30, v31
	global_store_dwordx2 v1, v[12:13], s[12:13]
	global_store_dwordx2 v1, v[14:15], s[12:13] offset:128
	s_add_u32 s12, s12, 0x700000
	s_addc_u32 s13, s13, 0
	v_cvt_f32_f16_e32 v16, v80
	v_cvt_f32_f16_sdwa v17, v80 dst_sel:DWORD dst_unused:UNUSED_PAD src0_sel:WORD_1
	v_cvt_f32_f16_e32 v20, v82
	v_cvt_f32_f16_sdwa v21, v82 dst_sel:DWORD dst_unused:UNUSED_PAD src0_sel:WORD_1
	v_cvt_f32_f16_e32 v18, v81
	v_cvt_f32_f16_sdwa v19, v81 dst_sel:DWORD dst_unused:UNUSED_PAD src0_sel:WORD_1
	v_cvt_f32_f16_e32 v22, v83
	v_cvt_f32_f16_sdwa v23, v83 dst_sel:DWORD dst_unused:UNUSED_PAD src0_sel:WORD_1
	v_pk_mul_f32 v[24:25], v[16:17], v[84:85]
	v_pk_mul_f32 v[28:29], v[16:17], v[88:89]
	v_pk_mul_f32 v[26:27], v[18:19], v[86:87]
	v_pk_mul_f32 v[30:31], v[18:19], v[90:91]
	v_pk_fma_f32 v[24:25], v[20:21], v[88:89], v[24:25] neg_lo:[1,0,0] neg_hi:[1,0,0]
	v_pk_fma_f32 v[28:29], v[20:21], v[84:85], v[28:29]
	v_pk_fma_f32 v[26:27], v[22:23], v[90:91], v[26:27] neg_lo:[1,0,0] neg_hi:[1,0,0]
	v_pk_fma_f32 v[30:31], v[22:23], v[86:87], v[30:31]
	v_pk_mul_f32 v[24:25], v[24:25], v[4:5]
	v_pk_mul_f32 v[28:29], v[28:29], v[4:5]
	v_pk_mul_f32 v[26:27], v[26:27], v[4:5]
	v_pk_mul_f32 v[30:31], v[30:31], v[4:5]
	v_cvt_pk_f16_f32 v8, v24, v25
	v_cvt_pk_f16_f32 v9, v26, v27
	v_cvt_pk_f16_f32 v10, v28, v29
	v_cvt_pk_f16_f32 v11, v30, v31
	global_store_dwordx2 v1, v[8:9], s[12:13]
	global_store_dwordx2 v1, v[10:11], s[12:13] offset:128
	s_add_u32 s12, s12, 0x700000
	s_addc_u32 s13, s13, 0
	v_cvt_f32_f16_e32 v16, v92
	v_cvt_f32_f16_sdwa v17, v92 dst_sel:DWORD dst_unused:UNUSED_PAD src0_sel:WORD_1
	v_cvt_f32_f16_e32 v20, v94
	v_cvt_f32_f16_sdwa v21, v94 dst_sel:DWORD dst_unused:UNUSED_PAD src0_sel:WORD_1
	v_cvt_f32_f16_e32 v18, v93
	v_cvt_f32_f16_sdwa v19, v93 dst_sel:DWORD dst_unused:UNUSED_PAD src0_sel:WORD_1
	v_cvt_f32_f16_e32 v22, v95
	v_cvt_f32_f16_sdwa v23, v95 dst_sel:DWORD dst_unused:UNUSED_PAD src0_sel:WORD_1
	v_pk_mul_f32 v[24:25], v[16:17], v[96:97]
	v_pk_mul_f32 v[28:29], v[16:17], v[100:101]
	v_pk_mul_f32 v[26:27], v[18:19], v[98:99]
	v_pk_mul_f32 v[30:31], v[18:19], v[102:103]
	v_pk_fma_f32 v[24:25], v[20:21], v[100:101], v[24:25] neg_lo:[1,0,0] neg_hi:[1,0,0]
	v_pk_fma_f32 v[28:29], v[20:21], v[96:97], v[28:29]
; #define TIDX tid_fn()
; __device__ __forceinline__ void row_decode(int row, int& isctx, int& b, int& t) {
;   if (row < NL) { isctx = 0; b = row / SEQ; t = row % SEQ; }
;   else { int r = row - NL; isctx = 1; b = r / CTX_LEN; t = r % CTX_LEN; }
; }
; __device__ __forceinline__ void ph_rope(const Params& P) {
;     ...
;   for (size_t i = (size_t)blockIdx.x * NTHR + TIDX; i < total; i += (size_t)gridDim.x * NTHR) {
;     const int row = (int)(i / PER_ROW), it = (int)(i % PER_ROW);
;     const int f4 = it % 16, hh = (it / 16) % RET_HEADS, qk = it / (16 * RET_HEADS);
;     int isc, b, t; row_decode(row, isc, b, t);
;     const int pos = isc ? SEQ + t : t;
;     h16* pr = p + (size_t)row * NP_EV + 3 * HY_CH + qk * RETW + hh * RET_HD + f4 * 4;
;     const h16x4 t1 = *(const h16x4*)pr, t2 = *(const h16x4*)(pr + 64);
;     const float4 c = *(const float4*)(rc + (size_t)pos * 64 + f4 * 4), s = *(const float4*)(rs + (size_t)pos * 64 + f4 * 4);
;     const float sc = qk ? kscale : 1.0f;
;     h16x4 o1, o2;
;     o1[0] = (h16)(((float)t1[0] * c.x - (float)t2[0] * s.x) * sc); o2[0] = (h16)(((float)t1[0] * s.x + (float)t2[0] * c.x) * sc);
;     o1[1] = (h16)(((float)t1[1] * c.y - (float)t2[1] * s.y) * sc); o2[1] = (h16)(((float)t1[1] * s.y + (float)t2[1] * c.y) * sc);
;     o1[2] = (h16)(((float)t1[2] * c.z - (float)t2[2] * s.z) * sc); o2[2] = (h16)(((float)t1[2] * s.z + (float)t2[2] * c.z) * sc);
;     o1[3] = (h16)(((float)t1[3] * c.w - (float)t2[3] * s.w) * sc); o2[3] = (h16)(((float)t1[3] * s.w + (float)t2[3] * c.w) * sc);
;     *(h16x4*)pr = o1; *(h16x4*)(pr + 64) = o2;
;   }
	v_pk_fma_f32 v[26:27], v[22:23], v[102:103], v[26:27] neg_lo:[1,0,0] neg_hi:[1,0,0]
	v_pk_fma_f32 v[30:31], v[22:23], v[98:99], v[30:31]
	v_pk_mul_f32 v[24:25], v[24:25], v[4:5]
	v_pk_mul_f32 v[28:29], v[28:29], v[4:5]
	v_pk_mul_f32 v[26:27], v[26:27], v[4:5]
	v_pk_mul_f32 v[30:31], v[30:31], v[4:5]
	v_cvt_pk_f16_f32 v12, v24, v25
	v_cvt_pk_f16_f32 v13, v26, v27
	v_cvt_pk_f16_f32 v14, v28, v29
	v_cvt_pk_f16_f32 v15, v30, v31
	global_store_dwordx2 v1, v[12:13], s[12:13]
	global_store_dwordx2 v1, v[14:15], s[12:13] offset:128
	s_add_u32 s12, s12, 0x700000
	s_addc_u32 s13, s13, 0
	v_cvt_f32_f16_e32 v16, v104
	v_cvt_f32_f16_sdwa v17, v104 dst_sel:DWORD dst_unused:UNUSED_PAD src0_sel:WORD_1
	v_cvt_f32_f16_e32 v20, v106
	v_cvt_f32_f16_sdwa v21, v106 dst_sel:DWORD dst_unused:UNUSED_PAD src0_sel:WORD_1
	v_cvt_f32_f16_e32 v18, v105
	v_cvt_f32_f16_sdwa v19, v105 dst_sel:DWORD dst_unused:UNUSED_PAD src0_sel:WORD_1
	v_cvt_f32_f16_e32 v22, v107
	v_cvt_f32_f16_sdwa v23, v107 dst_sel:DWORD dst_unused:UNUSED_PAD src0_sel:WORD_1
	v_pk_mul_f32 v[24:25], v[16:17], v[108:109]
	v_pk_mul_f32 v[28:29], v[16:17], v[112:113]
	v_pk_mul_f32 v[26:27], v[18:19], v[110:111]
	v_pk_mul_f32 v[30:31], v[18:19], v[114:115]
	v_pk_fma_f32 v[24:25], v[20:21], v[112:113], v[24:25] neg_lo:[1,0,0] neg_hi:[1,0,0]
	v_pk_fma_f32 v[28:29], v[20:21], v[108:109], v[28:29]
	v_pk_fma_f32 v[26:27], v[22:23], v[114:115], v[26:27] neg_lo:[1,0,0] neg_hi:[1,0,0]
	v_pk_fma_f32 v[30:31], v[22:23], v[110:111], v[30:31]
	v_pk_mul_f32 v[24:25], v[24:25], v[4:5]
	v_pk_mul_f32 v[28:29], v[28:29], v[4:5]
	v_pk_mul_f32 v[26:27], v[26:27], v[4:5]
	v_pk_mul_f32 v[30:31], v[30:31], v[4:5]
	v_cvt_pk_f16_f32 v8, v24, v25
	v_cvt_pk_f16_f32 v9, v26, v27
	v_cvt_pk_f16_f32 v10, v28, v29
	v_cvt_pk_f16_f32 v11, v30, v31
	global_store_dwordx2 v1, v[8:9], s[12:13]
	global_store_dwordx2 v1, v[10:11], s[12:13] offset:128
	s_add_u32 s12, s12, 0x700000
	s_addc_u32 s13, s13, 0
	v_cvt_f32_f16_e32 v16, v116
	v_cvt_f32_f16_sdwa v17, v116 dst_sel:DWORD dst_unused:UNUSED_PAD src0_sel:WORD_1
	v_cvt_f32_f16_e32 v20, v118
	v_cvt_f32_f16_sdwa v21, v118 dst_sel:DWORD dst_unused:UNUSED_PAD src0_sel:WORD_1
	v_cvt_f32_f16_e32 v18, v117
	v_cvt_f32_f16_sdwa v19, v117 dst_sel:DWORD dst_unused:UNUSED_PAD src0_sel:WORD_1
	v_cvt_f32_f16_e32 v22, v119
	v_cvt_f32_f16_sdwa v23, v119 dst_sel:DWORD dst_unused:UNUSED_PAD src0_sel:WORD_1
	v_pk_mul_f32 v[24:25], v[16:17], v[120:121]
	v_pk_mul_f32 v[28:29], v[16:17], v[124:125]
	v_pk_mul_f32 v[26:27], v[18:19], v[122:123]
	v_pk_mul_f32 v[30:31], v[18:19], v[126:127]
	v_pk_fma_f32 v[24:25], v[20:21], v[124:125], v[24:25] neg_lo:[1,0,0] neg_hi:[1,0,0]
	v_pk_fma_f32 v[28:29], v[20:21], v[120:121], v[28:29]
	v_pk_fma_f32 v[26:27], v[22:23], v[126:127], v[26:27] neg_lo:[1,0,0] neg_hi:[1,0,0]
	v_pk_fma_f32 v[30:31], v[22:23], v[122:123], v[30:31]
	v_pk_mul_f32 v[24:25], v[24:25], v[4:5]
	v_pk_mul_f32 v[28:29], v[28:29], v[4:5]
	v_pk_mul_f32 v[26:27], v[26:27], v[4:5]
	v_pk_mul_f32 v[30:31], v[30:31], v[4:5]
	v_cvt_pk_f16_f32 v12, v24, v25
	v_cvt_pk_f16_f32 v13, v26, v27
	v_cvt_pk_f16_f32 v14, v28, v29
	v_cvt_pk_f16_f32 v15, v30, v31
	global_store_dwordx2 v1, v[12:13], s[12:13]
	global_store_dwordx2 v1, v[14:15], s[12:13] offset:128
	s_add_u32 s12, s12, 0x700000
	s_addc_u32 s13, s13, 0
	s_and_b32 s0, s22, 0xff
	s_add_u32 s0, s0, 0x4000
	s_lshl_b32 s0, s0, 8
	s_add_u32 s14, s4, 0x4c000
	s_addc_u32 s15, s5, 0
	s_add_u32 s14, s14, s0
	s_addc_u32 s15, s15, 0
	s_add_u32 s16, s14, 0x410000
	s_addc_u32 s17, s15, 0
	global_load_dwordx2 v[32:33], v1, s[10:11]
	global_load_dwordx2 v[34:35], v1, s[10:11] offset:128
	global_load_dwordx4 v[36:39], v2, s[14:15]
	global_load_dwordx4 v[40:43], v2, s[16:17]
	s_add_u32 s10, s10, 0x700000
	s_addc_u32 s11, s11, 0
	s_add_u32 s14, s14, 0x20000
	s_addc_u32 s15, s15, 0
	s_add_u32 s16, s16, 0x20000
	s_addc_u32 s17, s17, 0
	s_waitcnt vmcnt(0)
	v_cvt_f32_f16_e32 v16, v32
	v_cvt_f32_f16_sdwa v17, v32 dst_sel:DWORD dst_unused:UNUSED_PAD src0_sel:WORD_1
	v_cvt_f32_f16_e32 v20, v34
	v_cvt_f32_f16_sdwa v21, v34 dst_sel:DWORD dst_unused:UNUSED_PAD src0_sel:WORD_1
	v_cvt_f32_f16_e32 v18, v33
	v_cvt_f32_f16_sdwa v19, v33 dst_sel:DWORD dst_unused:UNUSED_PAD src0_sel:WORD_1
	v_cvt_f32_f16_e32 v22, v35
	v_cvt_f32_f16_sdwa v23, v35 dst_sel:DWORD dst_unused:UNUSED_PAD src0_sel:WORD_1
	v_pk_mul_f32 v[24:25], v[16:17], v[36:37]
	v_pk_mul_f32 v[28:29], v[16:17], v[40:41]
	v_pk_mul_f32 v[26:27], v[18:19], v[38:39]
	v_pk_mul_f32 v[30:31], v[18:19], v[42:43]
	v_pk_fma_f32 v[24:25], v[20:21], v[40:41], v[24:25] neg_lo:[1,0,0] neg_hi:[1,0,0]
	v_pk_fma_f32 v[28:29], v[20:21], v[36:37], v[28:29]
	v_pk_fma_f32 v[26:27], v[22:23], v[42:43], v[26:27] neg_lo:[1,0,0] neg_hi:[1,0,0]
	v_pk_fma_f32 v[30:31], v[22:23], v[38:39], v[30:31]
	v_pk_mul_f32 v[24:25], v[24:25], v[4:5]
	v_pk_mul_f32 v[28:29], v[28:29], v[4:5]
	v_pk_mul_f32 v[26:27], v[26:27], v[4:5]
	v_pk_mul_f32 v[30:31], v[30:31], v[4:5]
	v_cvt_pk_f16_f32 v8, v24, v25
	v_cvt_pk_f16_f32 v9, v26, v27
	v_cvt_pk_f16_f32 v10, v28, v29
	v_cvt_pk_f16_f32 v11, v30, v31
	global_store_dwordx2 v1, v[8:9], s[12:13]
	global_store_dwordx2 v1, v[10:11], s[12:13] offset:128
	s_add_u32 s12, s12, 0x700000
	s_addc_u32 s13, s13, 0
